# combined: fox prologue hoist, ssd_out closing norm pipelined, hot loop headers aligned
# baseline (speedup 1.0000x reference)
; DI f32x4 mmaT(bf16x8 a_m, bf16x8 b_n, f32x4 c) { return __builtin_amdgcn_mfma_f32_16x16x32_bf16(b_n, a_m, c, 0, 0, 0); }
; DI void ret_out_unit(const Params& p, int hf, int bl, int c, int hd, unsigned char* shm, int tid, bool dry = false) {
;     ...
;   f32x4 o1[8];
; #pragma unroll
;   for (int n = 0; n < 8; ++n) o1[n] = (f32x4){0.f, 0.f, 0.f, 0.f};
;   const int nks = (wid >> 1) + 1;
;   for (int ks = 0; ks < nks; ++ks) {
;     const bf16x8 a = ldf(sS, LD, 16 * wid, 32 * ks, fr, fq);
; #pragma unroll
;     for (int n = 0; n < 8; ++n) o1[n] = mmaT(a, frag_tr(sVt, LD, 32 * ks, 16 * n, fr, fq), o1[n]);
;   }
.LBB0_463:
	s_or_b64 exec, exec, s[0:1]
	v_ashrrev_i32_e32 v77, 7, v66
	v_mov_b32_e32 v39, 0
	v_cmp_lt_i32_e32 vcc, -1, v77
	v_lshlrev_b32_e32 v76, 4, v75
	v_mov_b32_e32 v38, v39
	v_mov_b32_e32 v37, v39
	v_mov_b32_e32 v36, v39
	v_mov_b32_e32 v35, v39
	v_mov_b32_e32 v34, v39
	v_mov_b32_e32 v33, v39
	v_mov_b32_e32 v32, v39
	s_waitcnt lgkmcnt(3)
	v_mov_b32_e32 v31, v39
	v_mov_b32_e32 v30, v39
	v_mov_b32_e32 v29, v39
	v_mov_b32_e32 v28, v39
	s_waitcnt lgkmcnt(2)
	v_mov_b32_e32 v27, v39
	v_mov_b32_e32 v26, v39
	v_mov_b32_e32 v25, v39
	v_mov_b32_e32 v24, v39
	s_waitcnt lgkmcnt(1)
	v_mov_b32_e32 v23, v39
	v_mov_b32_e32 v22, v39
	v_mov_b32_e32 v21, v39
	v_mov_b32_e32 v20, v39
	s_waitcnt lgkmcnt(0)
	v_mov_b32_e32 v19, v39
	v_mov_b32_e32 v18, v39
	v_mov_b32_e32 v17, v39
	v_mov_b32_e32 v16, v39
	v_mov_b32_e32 v47, v39
	v_mov_b32_e32 v46, v39
	v_mov_b32_e32 v45, v39
	v_mov_b32_e32 v44, v39
	v_mov_b32_e32 v43, v39
	v_mov_b32_e32 v42, v39
	v_mov_b32_e32 v41, v39
	v_mov_b32_e32 v40, v39
	s_and_saveexec_b64 s[0:1], vcc
	s_cbranch_execz .LBB0_467
	v_lshrrev_b32_e32 v16, 2, v74
	v_and_b32_e32 v18, 3, v66
	v_mul_u32_u24_e32 v17, 0x880, v75
	v_mul_u32_u24_e32 v16, 0x110, v16
	v_lshlrev_b32_e32 v18, 3, v18
	s_movk_i32 s2, 0x1100
	v_add3_u32 v66, v17, v16, v18
	v_mul_lo_u32 v16, v73, s2
	v_mad_u32_u24 v16, v74, s66, v16
	s_mov_b32 s2, 0x19800
	v_mov_b32_e32 v40, 0
	v_add_u32_e32 v77, 1, v77
	v_add3_u32 v73, v16, v76, s2
	s_mov_b64 s[4:5], 0
	v_mov_b32_e32 v41, v40
	v_mov_b32_e32 v42, v40
	v_mov_b32_e32 v43, v40
	v_mov_b32_e32 v44, v40
	v_mov_b32_e32 v45, v40
	v_mov_b32_e32 v46, v40
	v_mov_b32_e32 v47, v40
	v_mov_b32_e32 v16, v40
	v_mov_b32_e32 v17, v40
	v_mov_b32_e32 v18, v40
	v_mov_b32_e32 v19, v40
	v_mov_b32_e32 v20, v40
	v_mov_b32_e32 v21, v40
	v_mov_b32_e32 v22, v40
	v_mov_b32_e32 v23, v40
	v_mov_b32_e32 v24, v40
	v_mov_b32_e32 v25, v40
	v_mov_b32_e32 v26, v40
	v_mov_b32_e32 v27, v40
	v_mov_b32_e32 v28, v40
	v_mov_b32_e32 v29, v40
	v_mov_b32_e32 v30, v40
	v_mov_b32_e32 v31, v40
	v_mov_b32_e32 v32, v40
	v_mov_b32_e32 v33, v40
	v_mov_b32_e32 v34, v40
	v_mov_b32_e32 v35, v40
	v_mov_b32_e32 v36, v40
	v_mov_b32_e32 v37, v40
	v_mov_b32_e32 v38, v40
	v_mov_b32_e32 v39, v40
	.p2align 6

; DI f32x4 mmaT(bf16x8 a_m, bf16x8 b_n, f32x4 c) { return __builtin_amdgcn_mfma_f32_16x16x32_bf16(b_n, a_m, c, 0, 0, 0); }
; DI void ssd_out_unit(const Params& p, int layer, int hf, int bl, int c, unsigned char* shm, int tid, bool dry = false) {
;     ...
;       bf16_t* zp = projb + (size_t)(c * 128 + i_row) * NP + C_Z + h * 64 + 4 * fq;
;       uint2 zv4[4];
; #pragma unroll
;       for (int m = 0; m < 4; ++m) zv4[m] = *(const uint2*)(zp + 16 * m);
;       __syncthreads();
;       f32x4 y[4], y2[4];
; #pragma unroll
;       for (int m = 0; m < 4; ++m) { y[m] = (f32x4){0.f, 0.f, 0.f, 0.f}; y2[m] = (f32x4){0.f, 0.f, 0.f, 0.f}; }
;       const int nks = (wid >> 1) + 1;
;       for (int ks = 0; ks < nks; ++ks) {
;         const bf16x8 a = ldf(sM, LD, 16 * wid, 32 * ks, fr, fq);
; #pragma unroll
;         for (int m = 0; m < 4; ++m) y[m] = mmaT(a, frag_tr(sX, LXS, 32 * ks, 16 * m, fr, fq), y[m]);
;       }
.LBB0_565:
	s_or_b64 exec, exec, s[30:31]
	s_lshl_b32 s2, s44, 7
	v_lshl_add_u64 v[106:107], v[88:89], 0, s[2:3]
	global_load_dwordx2 v[118:119], v[106:107], off
	global_load_dwordx2 v[114:115], v[106:107], off offset:32
	global_load_dwordx2 v[110:111], v[106:107], off offset:64
	global_load_dwordx2 v[108:109], v[106:107], off offset:96
	v_mov_b32_e32 v51, 0
	v_mov_b32_e32 v50, v51
	v_mov_b32_e32 v49, v51
	v_mov_b32_e32 v48, v51
	v_mov_b32_e32 v55, v51
	v_mov_b32_e32 v54, v51
	v_mov_b32_e32 v53, v51
	v_mov_b32_e32 v52, v51
	v_mov_b32_e32 v59, v51
	v_mov_b32_e32 v58, v51
	v_mov_b32_e32 v57, v51
	v_mov_b32_e32 v56, v51
	v_mov_b32_e32 v67, v51
	v_mov_b32_e32 v66, v51
	v_mov_b32_e32 v65, v51
	v_mov_b32_e32 v64, v51
	s_waitcnt lgkmcnt(0)
	s_barrier
	s_and_saveexec_b64 s[30:31], s[4:5]
	s_cbranch_execz .LBB0_520
	v_mov_b32_e32 v64, 0
	s_mov_b64 s[34:35], 0
	v_mov_b32_e32 v60, v131
	v_mov_b32_e32 v61, v130
	v_mov_b32_e32 v62, v129
	v_mov_b32_e32 v65, v64
	v_mov_b32_e32 v66, v64
	v_mov_b32_e32 v67, v64
	v_mov_b32_e32 v56, v64
	v_mov_b32_e32 v57, v64
	v_mov_b32_e32 v58, v64
	v_mov_b32_e32 v59, v64
	v_mov_b32_e32 v52, v64
	v_mov_b32_e32 v53, v64
	v_mov_b32_e32 v54, v64
	v_mov_b32_e32 v55, v64
	v_mov_b32_e32 v48, v64
	v_mov_b32_e32 v49, v64
	v_mov_b32_e32 v50, v64
	v_mov_b32_e32 v51, v64
	.p2align 6

; DI void ssd_out_unit(const Params& p, int layer, int hf, int bl, int c, unsigned char* shm, int tid, bool dry = false) {
;     ...
;   bf16_t* zr = projb + (size_t)(c * 128 + i_row) * NP + C_Z + 4 * fq;
;   for (int t0 = 0; t0 < 64; t0 += 8) {
;     uint2 v8[8]; float4 g8[8];
; #pragma unroll
;     for (int q = 0; q < 8; ++q) { v8[q] = *(const uint2*)(zr + 16 * (t0 + q)); g8[q] = *(const float4*)(gn + 16 * (t0 + q) + 4 * fq); }
.LBB0_570:
	v_lshl_add_u64 v[248:249], s[0:1], 0, v[160:161]
	global_load_dwordx2 v[144:145], v[20:21], off offset:-228
	global_load_dwordx4 v[172:175], v[248:249], off offset:-460
	global_load_dwordx2 v[146:147], v[20:21], off offset:-196
	global_load_dwordx4 v[176:179], v[248:249], off offset:-396
	global_load_dwordx2 v[148:149], v[20:21], off offset:-164
	global_load_dwordx4 v[180:183], v[248:249], off offset:-332
	global_load_dwordx2 v[150:151], v[20:21], off offset:-132
	global_load_dwordx4 v[184:187], v[248:249], off offset:-268
	global_load_dwordx2 v[152:153], v[20:21], off offset:-100
	global_load_dwordx4 v[188:191], v[248:249], off offset:-204
	global_load_dwordx2 v[154:155], v[20:21], off offset:-68
	global_load_dwordx4 v[236:239], v[248:249], off offset:-140
	global_load_dwordx2 v[156:157], v[20:21], off offset:-36
	global_load_dwordx4 v[240:243], v[248:249], off offset:-76
	global_load_dwordx2 v[158:159], v[20:21], off offset:-4
	global_load_dwordx4 v[244:247], v[248:249], off offset:-12
	global_load_dwordx2 v[22:23], v[20:21], off offset:28
	global_load_dwordx4 v[0:3], v[248:249], off offset:52
	global_load_dwordx2 v[24:25], v[20:21], off offset:60
	global_load_dwordx4 v[4:7], v[248:249], off offset:116
	global_load_dwordx2 v[26:27], v[20:21], off offset:92
	global_load_dwordx4 v[8:11], v[248:249], off offset:180
	global_load_dwordx2 v[28:29], v[20:21], off offset:124
	global_load_dwordx4 v[12:15], v[248:249], off offset:244
	global_load_dwordx2 v[30:31], v[20:21], off offset:156
	global_load_dwordx4 v[16:19], v[248:249], off offset:308
	global_load_dwordx2 v[46:47], v[20:21], off offset:188
	global_load_dwordx4 v[34:37], v[248:249], off offset:372
	global_load_dwordx2 v[48:49], v[20:21], off offset:220
	global_load_dwordx4 v[38:41], v[248:249], off offset:436
	global_load_dwordx2 v[50:51], v[20:21], off offset:252
	global_load_dwordx4 v[42:45], v[248:249], off offset:500
	s_mov_b32 s2, 0
	s_mov_b64 s[4:5], 0x200
	.p2align 6
